# P5 epilogue: hoist second-half b_gate loads before first-half stores (no store-ack wait), dynamic store-aware unit-start waits for P5
# speedup vs baseline: 1.0056x; 1.0021x over previous
.LBB0_1094:
	s_add_u32 s6, s6, 0x80
	s_addc_u32 s7, s7, 0
	s_add_u32 s10, s8, 0x100
	s_addc_u32 s11, s9, 0
	s_waitcnt lgkmcnt(0)
	ds_read_b128 v[128:131], v161
	ds_read_b128 v[132:135], v164
	ds_read_b128 v[150:153], v165
	ds_read_b128 v[154:157], v166
	ds_read_b128 v[182:185], v167
	ds_read_b128 v[186:189], v168
	ds_read_b128 v[190:193], v169
	ds_read_b128 v[194:197], v170
	s_add_i32 s77, s70, 2
	s_add_u32 s8, s6, 0x80
	s_addc_u32 s9, s7, 0
	s_cmp_eq_u32 s35, s70
	s_cselect_b32 s9, s79, s9
	s_cselect_b32 s8, s78, s8
	s_cselect_b32 s53, s83, s11
	s_cselect_b32 s52, s82, s10
	s_mov_b32 m0, s18
	v_lshl_add_u64 v[230:231], s[6:7], 0, v[144:145]
	ds_read_b128 v[198:201], v160
	ds_read_b128 v[202:205], v160 offset:1024
	ds_read_b128 v[206:209], v160 offset:2048
	ds_read_b128 v[210:213], v160 offset:3072
	ds_read_b128 v[214:217], v160 offset:4096
	ds_read_b128 v[218:221], v160 offset:5120
	ds_read_b128 v[222:225], v160 offset:6144
	ds_read_b128 v[226:229], v160 offset:7168
	global_load_lds_dwordx4 v[230:231], off
	v_lshl_add_u64 v[230:231], s[6:7], 0, v[146:147]
	s_mov_b32 m0, s19
	s_nop 0
	global_load_lds_dwordx4 v[230:231], off
	s_cmp_lt_u32 s99, 2
	s_cbranch_scc1 .Lsw_3_0_a
	s_cmp_eq_u32 s99, 2
	s_cbranch_scc1 .Lsw_3_0_b
	s_waitcnt vmcnt(24)
	s_branch .Lsw_3_0_c
.Lsw_3_0_b:
	s_waitcnt vmcnt(16)
	s_branch .Lsw_3_0_c
.Lsw_3_0_a:
	s_waitcnt vmcnt(8)
.Lsw_3_0_c:
	s_waitcnt lgkmcnt(0)
	s_barrier
	s_setprio 1
	s_waitcnt lgkmcnt(0)
	v_mfma_f32_16x16x32_bf16 v[112:115], v[128:131], v[198:201], 0
	v_mfma_f32_16x16x32_bf16 v[124:127], v[150:153], v[198:201], 0
	v_mfma_f32_16x16x32_bf16 v[120:123], v[128:131], v[206:209], 0
	v_mfma_f32_16x16x32_bf16 v[116:119], v[150:153], v[206:209], 0
	v_mfma_f32_16x16x32_bf16 v[108:111], v[128:131], v[214:217], 0
	v_mfma_f32_16x16x32_bf16 v[104:107], v[150:153], v[214:217], 0
	v_mfma_f32_16x16x32_bf16 v[92:95], v[128:131], v[222:225], 0
	v_mfma_f32_16x16x32_bf16 v[88:91], v[150:153], v[222:225], 0
	v_mfma_f32_16x16x32_bf16 v[112:115], v[132:135], v[202:205], v[112:115]
	v_mfma_f32_16x16x32_bf16 v[124:127], v[154:157], v[202:205], v[124:127]
	v_mfma_f32_16x16x32_bf16 v[120:123], v[132:135], v[210:213], v[120:123]
	v_mfma_f32_16x16x32_bf16 v[116:119], v[154:157], v[210:213], v[116:119]
	v_mfma_f32_16x16x32_bf16 v[108:111], v[132:135], v[218:221], v[108:111]
	v_mfma_f32_16x16x32_bf16 v[104:107], v[154:157], v[218:221], v[104:107]
	v_mfma_f32_16x16x32_bf16 v[92:95], v[132:135], v[226:229], v[92:95]
	v_mfma_f32_16x16x32_bf16 v[88:91], v[154:157], v[226:229], v[88:91]
	s_setprio 0
	s_setprio 1
	v_mfma_f32_16x16x32_bf16 v[100:103], v[182:185], v[198:201], 0
	v_mfma_f32_16x16x32_bf16 v[96:99], v[190:193], v[198:201], 0
	v_mfma_f32_16x16x32_bf16 v[84:87], v[182:185], v[206:209], 0
	v_mfma_f32_16x16x32_bf16 v[80:83], v[190:193], v[206:209], 0
	v_mfma_f32_16x16x32_bf16 v[76:79], v[182:185], v[214:217], 0
	v_mfma_f32_16x16x32_bf16 v[72:75], v[190:193], v[214:217], 0
	v_mfma_f32_16x16x32_bf16 v[60:63], v[182:185], v[222:225], 0
	v_mfma_f32_16x16x32_bf16 v[56:59], v[190:193], v[222:225], 0
	v_mfma_f32_16x16x32_bf16 v[100:103], v[186:189], v[202:205], v[100:103]
	v_mfma_f32_16x16x32_bf16 v[96:99], v[194:197], v[202:205], v[96:99]
	v_mfma_f32_16x16x32_bf16 v[84:87], v[186:189], v[210:213], v[84:87]
	v_mfma_f32_16x16x32_bf16 v[80:83], v[194:197], v[210:213], v[80:83]
	v_mfma_f32_16x16x32_bf16 v[76:79], v[186:189], v[218:221], v[76:79]
	v_mfma_f32_16x16x32_bf16 v[72:75], v[194:197], v[218:221], v[72:75]
	v_mfma_f32_16x16x32_bf16 v[60:63], v[186:189], v[226:229], v[60:63]
	v_mfma_f32_16x16x32_bf16 v[56:59], v[194:197], v[226:229], v[56:59]
	s_setprio 0
	s_barrier
	s_mov_b32 m0, s88
	v_lshl_add_u64 v[230:231], s[52:53], 0, v[138:139]
	v_lshl_add_u64 v[232:233], s[52:53], 0, v[142:143]
	s_add_u32 s52, s52, s12
	ds_read_b128 v[198:201], v160 offset:16384
	ds_read_b128 v[202:205], v160 offset:17408
	ds_read_b128 v[206:209], v160 offset:18432
	ds_read_b128 v[210:213], v160 offset:19456
	ds_read_b128 v[214:217], v160 offset:20480
	ds_read_b128 v[218:221], v160 offset:21504
	ds_read_b128 v[222:225], v160 offset:22528
	ds_read_b128 v[226:229], v160 offset:23552
	global_load_lds_dwordx4 v[230:231], off
	s_mov_b32 m0, s89
	s_addc_u32 s53, s53, s13
	global_load_lds_dwordx4 v[232:233], off
	v_lshl_add_u64 v[234:235], s[52:53], 0, v[138:139]
	s_mov_b32 m0, s91
	v_lshl_add_u64 v[236:237], s[52:53], 0, v[142:143]
	global_load_lds_dwordx4 v[234:235], off
	s_mov_b32 m0, s92
	v_lshl_add_u64 v[238:239], s[8:9], 0, v[136:137]
	global_load_lds_dwordx4 v[236:237], off
	s_mov_b32 m0, s3
	v_lshl_add_u64 v[240:241], s[8:9], 0, v[140:141]
	global_load_lds_dwordx4 v[238:239], off
	s_mov_b32 m0, s93
	s_nop 0
	global_load_lds_dwordx4 v[240:241], off
	s_cmp_lt_u32 s99, 2
	s_cbranch_scc1 .Lsw_3_1_a
	s_cmp_eq_u32 s99, 2
	s_cbranch_scc1 .Lsw_3_1_b
	s_waitcnt vmcnt(24)
	s_branch .Lsw_3_1_c

.Lsw_3_1_c:
	s_waitcnt lgkmcnt(0)
	s_barrier
	s_setprio 1
	s_waitcnt lgkmcnt(0)
	v_mfma_f32_16x16x32_bf16 v[68:71], v[128:131], v[198:201], 0
	v_mfma_f32_16x16x32_bf16 v[64:67], v[150:153], v[198:201], 0
	v_mfma_f32_16x16x32_bf16 v[52:55], v[128:131], v[206:209], 0
	v_mfma_f32_16x16x32_bf16 v[48:51], v[150:153], v[206:209], 0
	v_mfma_f32_16x16x32_bf16 v[44:47], v[128:131], v[214:217], 0
	v_mfma_f32_16x16x32_bf16 v[32:35], v[150:153], v[214:217], 0
	v_mfma_f32_16x16x32_bf16 v[24:27], v[128:131], v[222:225], 0
	v_mfma_f32_16x16x32_bf16 v[16:19], v[150:153], v[222:225], 0
	v_mfma_f32_16x16x32_bf16 v[68:71], v[132:135], v[202:205], v[68:71]
	v_mfma_f32_16x16x32_bf16 v[64:67], v[154:157], v[202:205], v[64:67]
	v_mfma_f32_16x16x32_bf16 v[52:55], v[132:135], v[210:213], v[52:55]
	v_mfma_f32_16x16x32_bf16 v[48:51], v[154:157], v[210:213], v[48:51]
	v_mfma_f32_16x16x32_bf16 v[44:47], v[132:135], v[218:221], v[44:47]
	v_mfma_f32_16x16x32_bf16 v[32:35], v[154:157], v[218:221], v[32:35]
	v_mfma_f32_16x16x32_bf16 v[24:27], v[132:135], v[226:229], v[24:27]
	v_mfma_f32_16x16x32_bf16 v[16:19], v[154:157], v[226:229], v[16:19]
	s_setprio 0
	s_setprio 1
	v_mfma_f32_16x16x32_bf16 v[40:43], v[182:185], v[198:201], 0
	v_mfma_f32_16x16x32_bf16 v[36:39], v[190:193], v[198:201], 0
	v_mfma_f32_16x16x32_bf16 v[28:31], v[182:185], v[206:209], 0
	v_mfma_f32_16x16x32_bf16 v[20:23], v[190:193], v[206:209], 0
	v_mfma_f32_16x16x32_bf16 v[12:15], v[182:185], v[214:217], 0
	v_mfma_f32_16x16x32_bf16 v[8:11], v[190:193], v[214:217], 0
	v_mfma_f32_16x16x32_bf16 v[4:7], v[182:185], v[222:225], 0
	v_mfma_f32_16x16x32_bf16 v[0:3], v[190:193], v[222:225], 0
	v_mfma_f32_16x16x32_bf16 v[40:43], v[186:189], v[202:205], v[40:43]
	v_mfma_f32_16x16x32_bf16 v[36:39], v[194:197], v[202:205], v[36:39]
	v_mfma_f32_16x16x32_bf16 v[28:31], v[186:189], v[210:213], v[28:31]
	v_mfma_f32_16x16x32_bf16 v[20:23], v[194:197], v[210:213], v[20:23]
	v_mfma_f32_16x16x32_bf16 v[12:15], v[186:189], v[218:221], v[12:15]
	v_mfma_f32_16x16x32_bf16 v[8:11], v[194:197], v[218:221], v[8:11]
	v_mfma_f32_16x16x32_bf16 v[4:7], v[186:189], v[226:229], v[4:7]
	v_mfma_f32_16x16x32_bf16 v[0:3], v[194:197], v[226:229], v[0:3]
	s_setprio 0
	s_barrier
	ds_read_b128 v[128:131], v171
	ds_read_b128 v[132:135], v172
	ds_read_b128 v[150:153], v173
	ds_read_b128 v[154:157], v174
	ds_read_b128 v[182:185], v175
	ds_read_b128 v[186:189], v176
	ds_read_b128 v[190:193], v177
	ds_read_b128 v[194:197], v178
	s_add_u32 s8, s8, s0
	s_addc_u32 s9, s9, s1
	s_mov_b32 m0, s94
	v_lshl_add_u64 v[242:243], s[8:9], 0, v[136:137]
	ds_read_b128 v[198:201], v160 offset:32768
	ds_read_b128 v[202:205], v160 offset:33792
	ds_read_b128 v[206:209], v160 offset:34816
	ds_read_b128 v[210:213], v160 offset:35840
	ds_read_b128 v[214:217], v160 offset:36864
	ds_read_b128 v[218:221], v160 offset:37888
	ds_read_b128 v[222:225], v160 offset:38912
	ds_read_b128 v[226:229], v160 offset:39936
	global_load_lds_dwordx4 v[242:243], off
	v_lshl_add_u64 v[242:243], s[8:9], 0, v[140:141]
	s_mov_b32 m0, s95
	s_nop 0
	global_load_lds_dwordx4 v[242:243], off
	s_waitcnt vmcnt(8)
	s_waitcnt lgkmcnt(0)
	s_barrier
	s_setprio 1
	s_waitcnt lgkmcnt(0)
	v_mfma_f32_16x16x32_bf16 v[112:115], v[128:131], v[198:201], v[112:115]
	v_mfma_f32_16x16x32_bf16 v[124:127], v[150:153], v[198:201], v[124:127]
	v_mfma_f32_16x16x32_bf16 v[120:123], v[128:131], v[206:209], v[120:123]
	v_mfma_f32_16x16x32_bf16 v[116:119], v[150:153], v[206:209], v[116:119]
	v_mfma_f32_16x16x32_bf16 v[108:111], v[128:131], v[214:217], v[108:111]
	v_mfma_f32_16x16x32_bf16 v[104:107], v[150:153], v[214:217], v[104:107]
	v_mfma_f32_16x16x32_bf16 v[92:95], v[128:131], v[222:225], v[92:95]
	v_mfma_f32_16x16x32_bf16 v[88:91], v[150:153], v[222:225], v[88:91]
	v_mfma_f32_16x16x32_bf16 v[112:115], v[132:135], v[202:205], v[112:115]
	v_mfma_f32_16x16x32_bf16 v[124:127], v[154:157], v[202:205], v[124:127]
	v_mfma_f32_16x16x32_bf16 v[120:123], v[132:135], v[210:213], v[120:123]
	v_mfma_f32_16x16x32_bf16 v[116:119], v[154:157], v[210:213], v[116:119]
	v_mfma_f32_16x16x32_bf16 v[108:111], v[132:135], v[218:221], v[108:111]
	v_mfma_f32_16x16x32_bf16 v[104:107], v[154:157], v[218:221], v[104:107]
	v_mfma_f32_16x16x32_bf16 v[92:95], v[132:135], v[226:229], v[92:95]
	v_mfma_f32_16x16x32_bf16 v[88:91], v[154:157], v[226:229], v[88:91]
	s_setprio 0
	s_setprio 1
	v_mfma_f32_16x16x32_bf16 v[100:103], v[182:185], v[198:201], v[100:103]
	v_mfma_f32_16x16x32_bf16 v[96:99], v[190:193], v[198:201], v[96:99]
	v_mfma_f32_16x16x32_bf16 v[84:87], v[182:185], v[206:209], v[84:87]
	v_mfma_f32_16x16x32_bf16 v[80:83], v[190:193], v[206:209], v[80:83]
	v_mfma_f32_16x16x32_bf16 v[76:79], v[182:185], v[214:217], v[76:79]
	v_mfma_f32_16x16x32_bf16 v[72:75], v[190:193], v[214:217], v[72:75]
	v_mfma_f32_16x16x32_bf16 v[60:63], v[182:185], v[222:225], v[60:63]
	v_mfma_f32_16x16x32_bf16 v[56:59], v[190:193], v[222:225], v[56:59]
	v_mfma_f32_16x16x32_bf16 v[100:103], v[186:189], v[202:205], v[100:103]
	v_mfma_f32_16x16x32_bf16 v[96:99], v[194:197], v[202:205], v[96:99]
	v_mfma_f32_16x16x32_bf16 v[84:87], v[186:189], v[210:213], v[84:87]
	v_mfma_f32_16x16x32_bf16 v[80:83], v[194:197], v[210:213], v[80:83]
	v_mfma_f32_16x16x32_bf16 v[76:79], v[186:189], v[218:221], v[76:79]
	v_mfma_f32_16x16x32_bf16 v[72:75], v[194:197], v[218:221], v[72:75]
	v_mfma_f32_16x16x32_bf16 v[60:63], v[186:189], v[226:229], v[60:63]
	v_mfma_f32_16x16x32_bf16 v[56:59], v[194:197], v[226:229], v[56:59]
	s_setprio 0
	s_barrier
	s_mov_b32 m0, s97
	v_lshl_add_u64 v[230:231], v[230:231], 0, s[46:47]
	ds_read_b128 v[198:201], v160 offset:49152
	ds_read_b128 v[202:205], v160 offset:50176
	ds_read_b128 v[206:209], v160 offset:51200
	ds_read_b128 v[210:213], v160 offset:52224
	ds_read_b128 v[214:217], v160 offset:53248
	ds_read_b128 v[218:221], v160 offset:54272
	ds_read_b128 v[222:225], v160 offset:55296
	ds_read_b128 v[226:229], v160 offset:56320
	global_load_lds_dwordx4 v[230:231], off
	v_lshl_add_u64 v[230:231], v[232:233], 0, s[46:47]
	s_mov_b32 m0, s96
	s_nop 0
	global_load_lds_dwordx4 v[230:231], off
	v_lshl_add_u64 v[230:231], v[234:235], 0, s[46:47]
	s_mov_b32 m0, s90
	s_nop 0
	global_load_lds_dwordx4 v[230:231], off
	v_lshl_add_u64 v[230:231], v[236:237], 0, s[46:47]
	s_mov_b32 m0, s28
	s_nop 0
	global_load_lds_dwordx4 v[230:231], off
	v_lshl_add_u64 v[230:231], v[238:239], 0, s[46:47]
	s_mov_b32 m0, s20
	s_nop 0
	global_load_lds_dwordx4 v[230:231], off
	v_lshl_add_u64 v[230:231], v[240:241], 0, s[46:47]
	s_mov_b32 m0, s21
	s_nop 0
	global_load_lds_dwordx4 v[230:231], off
	s_waitcnt vmcnt(8)
	s_waitcnt lgkmcnt(0)
	s_barrier
	s_setprio 1
	s_waitcnt lgkmcnt(0)
	v_mfma_f32_16x16x32_bf16 v[68:71], v[128:131], v[198:201], v[68:71]
	v_mfma_f32_16x16x32_bf16 v[64:67], v[150:153], v[198:201], v[64:67]
	v_mfma_f32_16x16x32_bf16 v[52:55], v[128:131], v[206:209], v[52:55]
	v_mfma_f32_16x16x32_bf16 v[48:51], v[150:153], v[206:209], v[48:51]
	v_mfma_f32_16x16x32_bf16 v[44:47], v[128:131], v[214:217], v[44:47]
	v_mfma_f32_16x16x32_bf16 v[32:35], v[150:153], v[214:217], v[32:35]
	v_mfma_f32_16x16x32_bf16 v[24:27], v[128:131], v[222:225], v[24:27]
	v_mfma_f32_16x16x32_bf16 v[16:19], v[150:153], v[222:225], v[16:19]
	v_mfma_f32_16x16x32_bf16 v[68:71], v[132:135], v[202:205], v[68:71]
	v_mfma_f32_16x16x32_bf16 v[64:67], v[154:157], v[202:205], v[64:67]
	v_mfma_f32_16x16x32_bf16 v[52:55], v[132:135], v[210:213], v[52:55]
	v_mfma_f32_16x16x32_bf16 v[48:51], v[154:157], v[210:213], v[48:51]
	v_mfma_f32_16x16x32_bf16 v[44:47], v[132:135], v[218:221], v[44:47]
	v_mfma_f32_16x16x32_bf16 v[32:35], v[154:157], v[218:221], v[32:35]
	v_mfma_f32_16x16x32_bf16 v[24:27], v[132:135], v[226:229], v[24:27]
	v_mfma_f32_16x16x32_bf16 v[16:19], v[154:157], v[226:229], v[16:19]
	s_setprio 0
	s_setprio 1
	v_mfma_f32_16x16x32_bf16 v[40:43], v[182:185], v[198:201], v[40:43]
	v_mfma_f32_16x16x32_bf16 v[36:39], v[190:193], v[198:201], v[36:39]
	v_mfma_f32_16x16x32_bf16 v[28:31], v[182:185], v[206:209], v[28:31]
	v_mfma_f32_16x16x32_bf16 v[20:23], v[190:193], v[206:209], v[20:23]
	v_mfma_f32_16x16x32_bf16 v[12:15], v[182:185], v[214:217], v[12:15]
	v_mfma_f32_16x16x32_bf16 v[8:11], v[190:193], v[214:217], v[8:11]
	v_mfma_f32_16x16x32_bf16 v[4:7], v[182:185], v[222:225], v[4:7]
	v_mfma_f32_16x16x32_bf16 v[0:3], v[190:193], v[222:225], v[0:3]
	v_mfma_f32_16x16x32_bf16 v[40:43], v[186:189], v[202:205], v[40:43]
	v_mfma_f32_16x16x32_bf16 v[36:39], v[194:197], v[202:205], v[36:39]
	v_mfma_f32_16x16x32_bf16 v[28:31], v[186:189], v[210:213], v[28:31]
	v_mfma_f32_16x16x32_bf16 v[20:23], v[194:197], v[210:213], v[20:23]
	v_mfma_f32_16x16x32_bf16 v[12:15], v[186:189], v[218:221], v[12:15]
	v_mfma_f32_16x16x32_bf16 v[8:11], v[194:197], v[218:221], v[8:11]
	v_mfma_f32_16x16x32_bf16 v[4:7], v[186:189], v[226:229], v[4:7]
	v_mfma_f32_16x16x32_bf16 v[0:3], v[194:197], v[226:229], v[0:3]
	s_setprio 0
	s_barrier
	s_add_u32 s6, s6, 0x100
	s_addc_u32 s7, s7, 0
	s_add_u32 s10, s10, 0x100
	s_addc_u32 s11, s11, 0
	s_cmp_ge_i32 s77, s29
	s_mov_b32 s70, s77
	s_cbranch_scc1 .Lkx_3

.LBB0_1104:
	s_cmp_lt_u32 s80, 10
	s_cbranch_scc1 .LBB0_1130
	s_cmpk_lt_i32 s76, 0x80
	s_cselect_b64 s[84:85], -1, 0
	s_lshl_b32 s6, s80, 8
	s_or_b32 s70, s6, s34
	v_lshlrev_b32_e32 v152, 3, v181
	v_add_u32_e32 v182, 0xfffff5e0, v152
	v_add_u32_e32 v151, s48, v150
	s_or_b32 s98, s70, 0x80
	s_cmpk_lt_u32 s98, 0x1220
	s_cselect_b64 s[100:101], -1, 0
	s_and_b64 s[100:101], s[100:101], s[84:85]
	s_andn2_b64 vcc, exec, s[100:101]
	s_cbranch_vccnz .Lpg_skip
	v_add_u32_e32 v244, s98, v182
	v_readlane_b32 s100, v247, 23
	v_readlane_b32 s101, v247, 24
	v_ashrrev_i32_e32 v245, 31, v244
	s_nop 1
	v_lshl_add_u64 v[244:245], v[244:245], 2, s[100:101]
	global_load_dwordx4 v[236:239], v[244:245], off offset:16
	global_load_dwordx4 v[240:243], v[244:245], off
.Lpg_skip:
	s_cmpk_lg_i32 s70, 0xa00
	s_mov_b64 s[6:7], -1
	s_cbranch_scc0 .LBB0_1109
	s_cmpk_lt_u32 s70, 0x1220
	s_cselect_b64 s[6:7], -1, 0
	s_and_b64 s[6:7], s[6:7], s[84:85]
	s_andn2_b64 vcc, exec, s[6:7]
	s_cbranch_vccnz .LBB0_1108
	v_add_u32_e32 v154, s70, v182
	v_readlane_b32 s52, v247, 17
	v_ashrrev_i32_e32 v155, 31, v154
	v_readlane_b32 s58, v247, 23
	v_readlane_b32 s59, v247, 24
	v_readlane_b32 s56, v247, 21
	v_readlane_b32 s57, v247, 22
	v_lshl_add_u64 v[132:133], v[154:155], 2, s[58:59]
	s_waitcnt lgkmcnt(0)
	global_load_dwordx4 v[128:131], v[132:133], off offset:16
	s_nop 0
	global_load_dwordx4 v[132:135], v[132:133], off
	v_lshlrev_b64 v[154:155], 1, v[154:155]
	v_readlane_b32 s64, v247, 29
	v_readlane_b32 s65, v247, 30
	v_readlane_b32 s56, v246, 14
	v_readlane_b32 s64, v246, 12
	v_readlane_b32 s58, v246, 16
	v_readlane_b32 s57, v246, 15
	v_readlane_b32 s65, v246, 13
	v_readlane_b32 s59, v246, 17
	v_readlane_b32 s53, v247, 18
	v_readlane_b32 s54, v247, 19
	v_readlane_b32 s55, v247, 20
	v_readlane_b32 s60, v247, 25
	v_readlane_b32 s61, v247, 26
	v_readlane_b32 s62, v247, 27
	v_readlane_b32 s63, v247, 28
	v_readlane_b32 s66, v247, 31
	v_readlane_b32 s67, v247, 32
	s_waitcnt vmcnt(0)
	v_pk_add_f32 v[186:187], v[126:127], v[130:131]
	v_pk_add_f32 v[156:157], v[114:115], v[134:135]
	v_pk_add_f32 v[184:185], v[112:113], v[132:133]
	v_mul_f32_e32 v156, 0xbfb8aa3b, v156
	v_exp_f32_e32 v156, v156
	v_mul_f32_e32 v153, 0xbfb8aa3b, v184
	v_mul_f32_e32 v184, 0xbfb8aa3b, v185
	v_exp_f32_e32 v184, v184
	v_add_f32_e32 v156, 1.0, v156
	v_rcp_f32_e32 v192, v156
	v_mul_f32_e32 v156, 0xbfb8aa3b, v186
	v_exp_f32_e32 v156, v156
	v_pk_add_f32 v[188:189], v[124:125], v[128:129]
	v_add_f32_e32 v184, 1.0, v184
	v_mul_f32_e32 v183, 0xbfb8aa3b, v188
	v_add_f32_e32 v156, 1.0, v156
	v_rcp_f32_e32 v193, v156
	v_mul_f32_e32 v156, 0xbfb8aa3b, v157
	v_exp_f32_e32 v156, v156
	v_rcp_f32_e32 v190, v184
	v_mul_f32_e32 v184, 0xbfb8aa3b, v189
	v_exp_f32_e32 v153, v153
	v_add_f32_e32 v156, 1.0, v156
	v_rcp_f32_e32 v186, v156
	v_mul_f32_e32 v156, 0xbfb8aa3b, v187
	v_exp_f32_e32 v183, v183
	v_exp_f32_e32 v184, v184
	v_exp_f32_e32 v156, v156
	v_add_f32_e32 v153, 1.0, v153
	v_add_f32_e32 v183, 1.0, v183
	v_add_f32_e32 v184, 1.0, v184
	v_add_f32_e32 v156, 1.0, v156
	v_rcp_f32_e32 v153, v153
	v_rcp_f32_e32 v183, v183
	v_rcp_f32_e32 v191, v184
	v_rcp_f32_e32 v187, v156
	v_lshl_add_u32 v156, s76, 8, v151
	v_ashrrev_i32_e32 v157, 31, v156
	v_lshlrev_b64 v[184:185], 12, v[156:157]
	v_lshl_add_u64 v[184:185], s[72:73], 0, v[184:185]
	v_lshl_add_u64 v[188:189], v[184:185], 0, v[154:155]
	v_cvt_pk_bf16_f32 v184, v153, v190
	v_cvt_pk_bf16_f32 v185, v192, v186
	v_cvt_pk_bf16_f32 v186, v183, v191
	v_cvt_pk_bf16_f32 v187, v193, v187
	global_store_dwordx4 v[188:189], v[184:187], off
	v_pk_add_f32 v[188:189], v[118:119], v[130:131]
	v_pk_add_f32 v[190:191], v[116:117], v[128:129]
	v_pk_add_f32 v[184:185], v[122:123], v[134:135]
	v_pk_add_f32 v[186:187], v[120:121], v[132:133]
	v_mul_f32_e32 v184, 0xbfb8aa3b, v184
	v_exp_f32_e32 v184, v184
	v_mul_f32_e32 v183, 0xbfb8aa3b, v187
	v_mul_f32_e32 v157, 0xbfb8aa3b, v190
	v_mul_f32_e32 v153, 0xbfb8aa3b, v186
	v_add_f32_e32 v184, 1.0, v184
	v_rcp_f32_e32 v187, v184
	v_mul_f32_e32 v184, 0xbfb8aa3b, v188
	v_exp_f32_e32 v184, v184
	v_mul_f32_e32 v186, 0xbfb8aa3b, v191
	v_exp_f32_e32 v153, v153
	v_exp_f32_e32 v157, v157
	v_add_f32_e32 v184, 1.0, v184
	v_rcp_f32_e32 v190, v184
	v_mul_f32_e32 v184, 0xbfb8aa3b, v185
	v_exp_f32_e32 v184, v184
	v_exp_f32_e32 v183, v183
	v_exp_f32_e32 v186, v186
	v_add_f32_e32 v153, 1.0, v153
	v_add_f32_e32 v184, 1.0, v184
	v_rcp_f32_e32 v191, v184
	v_mul_f32_e32 v184, 0xbfb8aa3b, v189
	v_exp_f32_e32 v184, v184
	v_add_f32_e32 v157, 1.0, v157
	v_add_f32_e32 v183, 1.0, v183
	v_add_f32_e32 v186, 1.0, v186
	v_add_f32_e32 v184, 1.0, v184
	v_rcp_f32_e32 v153, v153
	v_rcp_f32_e32 v157, v157
	v_rcp_f32_e32 v183, v183
	v_rcp_f32_e32 v186, v186
	v_rcp_f32_e32 v192, v184
	v_add_u32_e32 v184, 16, v156
	v_ashrrev_i32_e32 v185, 31, v184
	v_lshlrev_b64 v[184:185], 12, v[184:185]
	v_lshl_add_u64 v[184:185], s[72:73], 0, v[184:185]
	v_lshl_add_u64 v[188:189], v[184:185], 0, v[154:155]
	v_cvt_pk_bf16_f32 v184, v153, v183
	v_cvt_pk_bf16_f32 v185, v187, v191
	v_cvt_pk_bf16_f32 v186, v157, v186
	v_cvt_pk_bf16_f32 v187, v190, v192
	global_store_dwordx4 v[188:189], v[184:187], off
	v_pk_add_f32 v[188:189], v[106:107], v[130:131]
	v_pk_add_f32 v[190:191], v[104:105], v[128:129]
	v_pk_add_f32 v[184:185], v[110:111], v[134:135]
	v_pk_add_f32 v[186:187], v[108:109], v[132:133]
	v_mul_f32_e32 v184, 0xbfb8aa3b, v184
	v_exp_f32_e32 v184, v184
	v_mul_f32_e32 v183, 0xbfb8aa3b, v187
	v_mul_f32_e32 v157, 0xbfb8aa3b, v190
	v_mul_f32_e32 v153, 0xbfb8aa3b, v186
	v_add_f32_e32 v184, 1.0, v184
	v_rcp_f32_e32 v187, v184
	v_mul_f32_e32 v184, 0xbfb8aa3b, v188
	v_exp_f32_e32 v184, v184
	v_mul_f32_e32 v186, 0xbfb8aa3b, v191
	v_exp_f32_e32 v153, v153
	v_exp_f32_e32 v157, v157
	v_add_f32_e32 v184, 1.0, v184
	v_rcp_f32_e32 v190, v184
	v_mul_f32_e32 v184, 0xbfb8aa3b, v185
	v_exp_f32_e32 v184, v184
	v_exp_f32_e32 v183, v183
	v_exp_f32_e32 v186, v186
	v_add_f32_e32 v153, 1.0, v153
	v_add_f32_e32 v184, 1.0, v184
	v_rcp_f32_e32 v191, v184
	v_mul_f32_e32 v184, 0xbfb8aa3b, v189
	v_exp_f32_e32 v184, v184
	v_add_f32_e32 v157, 1.0, v157
	v_add_f32_e32 v183, 1.0, v183
	v_add_f32_e32 v186, 1.0, v186
	v_add_f32_e32 v184, 1.0, v184
	v_rcp_f32_e32 v153, v153
	v_rcp_f32_e32 v157, v157
	v_rcp_f32_e32 v183, v183
	v_rcp_f32_e32 v186, v186
	v_rcp_f32_e32 v192, v184
	v_add_u32_e32 v184, 32, v156
	v_ashrrev_i32_e32 v185, 31, v184
	v_lshlrev_b64 v[184:185], 12, v[184:185]
	v_lshl_add_u64 v[184:185], s[72:73], 0, v[184:185]
	v_lshl_add_u64 v[188:189], v[184:185], 0, v[154:155]
	v_cvt_pk_bf16_f32 v184, v153, v183
	v_cvt_pk_bf16_f32 v185, v187, v191
	v_cvt_pk_bf16_f32 v186, v157, v186
	v_cvt_pk_bf16_f32 v187, v190, v192
	global_store_dwordx4 v[188:189], v[184:187], off
	v_pk_add_f32 v[188:189], v[90:91], v[130:131]
	v_pk_add_f32 v[190:191], v[88:89], v[128:129]
	v_pk_add_f32 v[184:185], v[94:95], v[134:135]
	v_pk_add_f32 v[186:187], v[92:93], v[132:133]
	v_mul_f32_e32 v184, 0xbfb8aa3b, v184
	v_exp_f32_e32 v184, v184
	v_mul_f32_e32 v183, 0xbfb8aa3b, v187
	v_mul_f32_e32 v157, 0xbfb8aa3b, v190
	v_mul_f32_e32 v153, 0xbfb8aa3b, v186
	v_add_f32_e32 v184, 1.0, v184
	v_rcp_f32_e32 v187, v184
	v_mul_f32_e32 v184, 0xbfb8aa3b, v188
	v_exp_f32_e32 v184, v184
	v_mul_f32_e32 v186, 0xbfb8aa3b, v191
	v_exp_f32_e32 v153, v153
	v_exp_f32_e32 v157, v157
	v_add_f32_e32 v184, 1.0, v184
	v_rcp_f32_e32 v190, v184
	v_mul_f32_e32 v184, 0xbfb8aa3b, v185
	v_exp_f32_e32 v184, v184
	v_exp_f32_e32 v183, v183
	v_exp_f32_e32 v186, v186
	v_add_f32_e32 v153, 1.0, v153
	v_add_f32_e32 v184, 1.0, v184
	v_rcp_f32_e32 v191, v184
	v_mul_f32_e32 v184, 0xbfb8aa3b, v189
	v_exp_f32_e32 v184, v184
	v_add_f32_e32 v157, 1.0, v157
	v_add_f32_e32 v183, 1.0, v183
	v_add_f32_e32 v186, 1.0, v186
	v_add_f32_e32 v184, 1.0, v184
	v_rcp_f32_e32 v153, v153
	v_rcp_f32_e32 v157, v157
	v_rcp_f32_e32 v183, v183
	v_rcp_f32_e32 v186, v186
	v_rcp_f32_e32 v192, v184
	v_add_u32_e32 v184, 48, v156
	v_ashrrev_i32_e32 v185, 31, v184
	v_lshlrev_b64 v[184:185], 12, v[184:185]
	v_lshl_add_u64 v[184:185], s[72:73], 0, v[184:185]
	v_lshl_add_u64 v[188:189], v[184:185], 0, v[154:155]
	v_cvt_pk_bf16_f32 v184, v153, v183
	v_cvt_pk_bf16_f32 v185, v187, v191
	v_cvt_pk_bf16_f32 v186, v157, v186
	v_cvt_pk_bf16_f32 v187, v190, v192
	global_store_dwordx4 v[188:189], v[184:187], off
	v_pk_add_f32 v[188:189], v[66:67], v[130:131]
	v_pk_add_f32 v[190:191], v[64:65], v[128:129]
	v_pk_add_f32 v[184:185], v[70:71], v[134:135]
	v_pk_add_f32 v[186:187], v[68:69], v[132:133]
	v_mul_f32_e32 v184, 0xbfb8aa3b, v184
	v_exp_f32_e32 v184, v184
	v_mul_f32_e32 v183, 0xbfb8aa3b, v187
	v_mul_f32_e32 v157, 0xbfb8aa3b, v190
	v_mul_f32_e32 v153, 0xbfb8aa3b, v186
	v_add_f32_e32 v184, 1.0, v184
	v_rcp_f32_e32 v187, v184
	v_mul_f32_e32 v184, 0xbfb8aa3b, v188
	v_exp_f32_e32 v184, v184
	v_mul_f32_e32 v186, 0xbfb8aa3b, v191
	v_exp_f32_e32 v153, v153
	v_exp_f32_e32 v157, v157
	v_add_f32_e32 v184, 1.0, v184
	v_rcp_f32_e32 v190, v184
	v_mul_f32_e32 v184, 0xbfb8aa3b, v185
	v_exp_f32_e32 v184, v184
	v_exp_f32_e32 v183, v183
	v_exp_f32_e32 v186, v186
	v_add_f32_e32 v153, 1.0, v153
	v_add_f32_e32 v184, 1.0, v184
	v_rcp_f32_e32 v191, v184
	v_mul_f32_e32 v184, 0xbfb8aa3b, v189
	v_exp_f32_e32 v184, v184
	v_add_f32_e32 v157, 1.0, v157
	v_add_f32_e32 v183, 1.0, v183
	v_add_f32_e32 v186, 1.0, v186
	v_add_f32_e32 v184, 1.0, v184
	v_rcp_f32_e32 v153, v153
	v_rcp_f32_e32 v157, v157
	v_rcp_f32_e32 v183, v183
	v_rcp_f32_e32 v186, v186
	v_rcp_f32_e32 v192, v184
	v_add_u32_e32 v184, 0x80, v156
	v_ashrrev_i32_e32 v185, 31, v184
	v_lshlrev_b64 v[184:185], 12, v[184:185]
	v_lshl_add_u64 v[184:185], s[72:73], 0, v[184:185]
	v_lshl_add_u64 v[188:189], v[184:185], 0, v[154:155]
	v_cvt_pk_bf16_f32 v184, v153, v183
	v_cvt_pk_bf16_f32 v185, v187, v191
	v_cvt_pk_bf16_f32 v186, v157, v186
	v_cvt_pk_bf16_f32 v187, v190, v192
	global_store_dwordx4 v[188:189], v[184:187], off
	v_pk_add_f32 v[188:189], v[50:51], v[130:131]
	v_pk_add_f32 v[190:191], v[48:49], v[128:129]
	v_pk_add_f32 v[184:185], v[54:55], v[134:135]
	v_pk_add_f32 v[186:187], v[52:53], v[132:133]
	v_mul_f32_e32 v184, 0xbfb8aa3b, v184
	v_exp_f32_e32 v184, v184
	v_mul_f32_e32 v183, 0xbfb8aa3b, v187
	v_mul_f32_e32 v157, 0xbfb8aa3b, v190
	v_mul_f32_e32 v153, 0xbfb8aa3b, v186
	v_add_f32_e32 v184, 1.0, v184
	v_rcp_f32_e32 v187, v184
	v_mul_f32_e32 v184, 0xbfb8aa3b, v188
	v_exp_f32_e32 v184, v184
	v_mul_f32_e32 v186, 0xbfb8aa3b, v191
	v_exp_f32_e32 v153, v153
	v_exp_f32_e32 v157, v157
	v_add_f32_e32 v184, 1.0, v184
	v_rcp_f32_e32 v190, v184
	v_mul_f32_e32 v184, 0xbfb8aa3b, v185
	v_exp_f32_e32 v184, v184
	v_exp_f32_e32 v183, v183
	v_exp_f32_e32 v186, v186
	v_add_f32_e32 v153, 1.0, v153
	v_add_f32_e32 v184, 1.0, v184
	v_rcp_f32_e32 v191, v184
	v_mul_f32_e32 v184, 0xbfb8aa3b, v189
	v_exp_f32_e32 v184, v184
	v_add_f32_e32 v157, 1.0, v157
	v_add_f32_e32 v183, 1.0, v183
	v_add_f32_e32 v186, 1.0, v186
	v_add_f32_e32 v184, 1.0, v184
	v_rcp_f32_e32 v153, v153
	v_rcp_f32_e32 v157, v157
	v_rcp_f32_e32 v183, v183
	v_rcp_f32_e32 v186, v186
	v_rcp_f32_e32 v192, v184
	v_add_u32_e32 v184, 0x90, v156
	v_ashrrev_i32_e32 v185, 31, v184
	v_lshlrev_b64 v[184:185], 12, v[184:185]
	v_lshl_add_u64 v[184:185], s[72:73], 0, v[184:185]
	v_lshl_add_u64 v[188:189], v[184:185], 0, v[154:155]
	v_cvt_pk_bf16_f32 v184, v153, v183
	v_cvt_pk_bf16_f32 v185, v187, v191
	v_cvt_pk_bf16_f32 v186, v157, v186
	v_cvt_pk_bf16_f32 v187, v190, v192
	global_store_dwordx4 v[188:189], v[184:187], off
	v_pk_add_f32 v[188:189], v[34:35], v[130:131]
	v_pk_add_f32 v[190:191], v[32:33], v[128:129]
	v_pk_add_f32 v[184:185], v[46:47], v[134:135]
	v_pk_add_f32 v[186:187], v[44:45], v[132:133]
	v_mul_f32_e32 v184, 0xbfb8aa3b, v184
	v_exp_f32_e32 v184, v184
	v_mul_f32_e32 v183, 0xbfb8aa3b, v187
	v_mul_f32_e32 v153, 0xbfb8aa3b, v186
	v_mul_f32_e32 v157, 0xbfb8aa3b, v190
	v_add_f32_e32 v184, 1.0, v184
	v_rcp_f32_e32 v187, v184
	v_mul_f32_e32 v184, 0xbfb8aa3b, v188
	v_exp_f32_e32 v184, v184
	v_mul_f32_e32 v186, 0xbfb8aa3b, v191
	v_exp_f32_e32 v157, v157
	v_exp_f32_e32 v186, v186
	v_add_f32_e32 v184, 1.0, v184
	v_rcp_f32_e32 v190, v184
	v_mul_f32_e32 v184, 0xbfb8aa3b, v185
	v_exp_f32_e32 v184, v184
	v_pk_add_f32 v[128:129], v[16:17], v[128:129]
	v_add_f32_e32 v157, 1.0, v157
	v_mul_f32_e32 v128, 0xbfb8aa3b, v128
	v_add_f32_e32 v186, 1.0, v186
	v_add_f32_e32 v184, 1.0, v184
	v_exp_f32_e32 v128, v128
	v_rcp_f32_e32 v157, v157
	v_rcp_f32_e32 v186, v186
	v_rcp_f32_e32 v191, v184
	v_mul_f32_e32 v184, 0xbfb8aa3b, v189
	v_exp_f32_e32 v153, v153
	v_exp_f32_e32 v183, v183
	v_exp_f32_e32 v184, v184
	v_pk_add_f32 v[132:133], v[24:25], v[132:133]
	v_add_f32_e32 v128, 1.0, v128
	v_cvt_pk_bf16_f32 v186, v157, v186
	v_rcp_f32_e32 v157, v128
	v_mul_f32_e32 v128, 0xbfb8aa3b, v133
	v_add_f32_e32 v153, 1.0, v153
	v_add_f32_e32 v183, 1.0, v183
	v_add_f32_e32 v184, 1.0, v184
	v_exp_f32_e32 v128, v128
	v_rcp_f32_e32 v153, v153
	v_rcp_f32_e32 v183, v183
	v_rcp_f32_e32 v192, v184
	v_add_u32_e32 v184, 0xa0, v156
	v_ashrrev_i32_e32 v185, 31, v184
	v_lshlrev_b64 v[184:185], 12, v[184:185]
	v_lshl_add_u64 v[184:185], s[72:73], 0, v[184:185]
	v_add_f32_e32 v128, 1.0, v128
	v_lshl_add_u64 v[188:189], v[184:185], 0, v[154:155]
	v_cvt_pk_bf16_f32 v184, v153, v183
	v_rcp_f32_e32 v183, v128
	v_mul_f32_e32 v128, 0xbfb8aa3b, v129
	v_exp_f32_e32 v128, v128
	v_cvt_pk_bf16_f32 v185, v187, v191
	v_cvt_pk_bf16_f32 v187, v190, v192
	v_pk_add_f32 v[134:135], v[26:27], v[134:135]
	v_add_f32_e32 v128, 1.0, v128
	global_store_dwordx4 v[188:189], v[184:187], off
	v_pk_add_f32 v[130:131], v[18:19], v[130:131]
	v_mul_f32_e32 v132, 0xbfb8aa3b, v132
	v_rcp_f32_e32 v184, v128
	v_mul_f32_e32 v128, 0xbfb8aa3b, v134
	v_exp_f32_e32 v128, v128
	v_exp_f32_e32 v132, v132
	v_add_f32_e32 v128, 1.0, v128
	v_rcp_f32_e32 v134, v128
	v_mul_f32_e32 v128, 0xbfb8aa3b, v130
	v_exp_f32_e32 v128, v128
	v_add_f32_e32 v132, 1.0, v132
	v_rcp_f32_e32 v153, v132
	v_add_f32_e32 v128, 1.0, v128
	v_rcp_f32_e32 v185, v128
	v_mul_f32_e32 v128, 0xbfb8aa3b, v135
	v_exp_f32_e32 v128, v128
	s_nop 0
	v_add_f32_e32 v128, 1.0, v128
	v_rcp_f32_e32 v130, v128
	v_mul_f32_e32 v128, 0xbfb8aa3b, v131
	v_exp_f32_e32 v128, v128
	s_nop 0
	v_add_f32_e32 v128, 1.0, v128
	v_rcp_f32_e32 v131, v128
	v_add_u32_e32 v128, 0xb0, v156
	v_ashrrev_i32_e32 v129, 31, v128
	v_lshlrev_b64 v[128:129], 12, v[128:129]
	v_lshl_add_u64 v[128:129], s[72:73], 0, v[128:129]
	v_lshl_add_u64 v[132:133], v[128:129], 0, v[154:155]
	v_cvt_pk_bf16_f32 v128, v153, v183
	v_cvt_pk_bf16_f32 v129, v134, v130
	v_cvt_pk_bf16_f32 v130, v157, v184
	v_cvt_pk_bf16_f32 v131, v185, v131
	global_store_dwordx4 v[132:133], v[128:131], off
	s_mov_b32 s99, 2

.LBB0_1126:
	v_ashrrev_i32_e32 v155, 31, v154
	v_lshlrev_b64 v[154:155], 6, v[154:155]
	v_lshl_add_u64 v[154:155], s[74:75], 0, v[154:155]
	v_lshl_add_u64 v[152:153], v[152:153], 1, v[154:155]
	v_cvt_pk_bf16_f32 v128, v128, v129
	v_cvt_pk_bf16_f32 v129, v130, v131
	v_cvt_pk_bf16_f32 v130, v132, v133
	v_cvt_pk_bf16_f32 v131, v134, v135
	global_store_dwordx4 v[152:153], v[128:131], off
	s_mov_b32 s99, 2
.LBB0_1127:
	s_bitset1_b32 s70, 7
	s_cmpk_lt_u32 s70, 0x1220
	s_cselect_b64 s[6:7], -1, 0
	s_and_b64 s[6:7], s[6:7], s[84:85]
	s_andn2_b64 vcc, exec, s[6:7]
	s_cbranch_vccnz .LBB0_1129
	v_add_u32_e32 v152, s70, v182
	v_readlane_b32 s52, v247, 17
	v_ashrrev_i32_e32 v153, 31, v152
	v_readlane_b32 s58, v247, 23
	v_readlane_b32 s59, v247, 24
	v_readlane_b32 s56, v247, 21
	v_readlane_b32 s57, v247, 22
	v_lshl_add_u64 v[132:133], v[152:153], 2, s[58:59]
	s_waitcnt lgkmcnt(0)
	v_lshlrev_b64 v[152:153], 1, v[152:153]
	v_readlane_b32 s64, v247, 29
	v_readlane_b32 s65, v247, 30
	v_readlane_b32 s56, v246, 14
	v_readlane_b32 s64, v246, 12
	v_readlane_b32 s58, v246, 16
	v_readlane_b32 s57, v246, 15
	v_readlane_b32 s65, v246, 13
	v_readlane_b32 s59, v246, 17
	v_readlane_b32 s53, v247, 18
	v_readlane_b32 s54, v247, 19
	v_readlane_b32 s55, v247, 20
	v_readlane_b32 s60, v247, 25
	v_readlane_b32 s61, v247, 26
	v_readlane_b32 s62, v247, 27
	v_readlane_b32 s63, v247, 28
	v_readlane_b32 s66, v247, 31
	v_readlane_b32 s67, v247, 32
	s_waitcnt vmcnt(8)
	v_mov_b64_e32 v[128:129], v[236:237]
	v_mov_b64_e32 v[130:131], v[238:239]
	v_mov_b64_e32 v[132:133], v[240:241]
	v_mov_b64_e32 v[134:135], v[242:243]
	v_pk_add_f32 v[182:183], v[98:99], v[130:131]
	v_pk_add_f32 v[154:155], v[102:103], v[134:135]
	v_pk_add_f32 v[156:157], v[100:101], v[132:133]
	v_mul_f32_e32 v154, 0xbfb8aa3b, v154
	v_mul_f32_e32 v156, 0xbfb8aa3b, v156
	v_exp_f32_e32 v156, v156
	v_exp_f32_e32 v154, v154
	v_pk_add_f32 v[184:185], v[96:97], v[128:129]
	v_add_f32_e32 v156, 1.0, v156
	v_add_f32_e32 v154, 1.0, v154
	v_rcp_f32_e32 v186, v156
	v_mul_f32_e32 v156, 0xbfb8aa3b, v184
	v_rcp_f32_e32 v188, v154
	v_mul_f32_e32 v154, 0xbfb8aa3b, v182
	v_exp_f32_e32 v156, v156
	v_exp_f32_e32 v154, v154
	v_add_f32_e32 v156, 1.0, v156
	v_add_f32_e32 v154, 1.0, v154
	v_rcp_f32_e32 v184, v156
	v_mul_f32_e32 v156, 0xbfb8aa3b, v157
	v_rcp_f32_e32 v189, v154
	v_mul_f32_e32 v154, 0xbfb8aa3b, v155
	v_exp_f32_e32 v156, v156
	v_exp_f32_e32 v154, v154
	v_add_f32_e32 v156, 1.0, v156
	v_add_f32_e32 v154, 1.0, v154
	v_rcp_f32_e32 v187, v156
	v_mul_f32_e32 v156, 0xbfb8aa3b, v185
	v_rcp_f32_e32 v190, v154
	v_mul_f32_e32 v154, 0xbfb8aa3b, v183
	v_exp_f32_e32 v156, v156
	v_exp_f32_e32 v154, v154
	v_cvt_pk_bf16_f32 v182, v186, v187
	v_cvt_pk_bf16_f32 v183, v188, v190
	v_add_f32_e32 v156, 1.0, v156
	v_add_f32_e32 v154, 1.0, v154
	v_rcp_f32_e32 v185, v156
	v_rcp_f32_e32 v191, v154
	v_lshl_add_u32 v154, s76, 8, v151
	v_ashrrev_i32_e32 v155, 31, v154
	v_lshlrev_b64 v[156:157], 12, v[154:155]
	v_lshl_add_u64 v[156:157], s[72:73], 0, v[156:157]
	v_lshl_add_u64 v[156:157], v[156:157], 0, v[152:153]
	v_cvt_pk_bf16_f32 v184, v184, v185
	v_cvt_pk_bf16_f32 v185, v189, v191
	global_store_dwordx4 v[156:157], v[182:185], off
	v_pk_add_f32 v[156:157], v[86:87], v[134:135]
	v_pk_add_f32 v[186:187], v[80:81], v[128:129]
	v_pk_add_f32 v[182:183], v[84:85], v[132:133]
	v_mul_f32_e32 v156, 0xbfb8aa3b, v156
	v_mul_f32_e32 v151, 0xbfb8aa3b, v182
	v_mul_f32_e32 v182, 0xbfb8aa3b, v183
	v_mul_f32_e32 v183, 0xbfb8aa3b, v187
	v_exp_f32_e32 v183, v183
	v_exp_f32_e32 v156, v156
	v_pk_add_f32 v[184:185], v[82:83], v[130:131]
	v_mul_f32_e32 v155, 0xbfb8aa3b, v186
	v_add_f32_e32 v183, 1.0, v183
	v_add_f32_e32 v156, 1.0, v156
	v_rcp_f32_e32 v186, v183
	v_rcp_f32_e32 v183, v156
	v_mul_f32_e32 v156, 0xbfb8aa3b, v184
	v_exp_f32_e32 v156, v156
	v_exp_f32_e32 v151, v151
	v_exp_f32_e32 v155, v155
	v_exp_f32_e32 v182, v182
	v_add_f32_e32 v156, 1.0, v156
	v_rcp_f32_e32 v187, v156
	v_mul_f32_e32 v156, 0xbfb8aa3b, v157
	v_exp_f32_e32 v156, v156
	v_add_f32_e32 v151, 1.0, v151
	v_add_f32_e32 v155, 1.0, v155
	v_add_f32_e32 v182, 1.0, v182
	v_add_f32_e32 v156, 1.0, v156
	v_rcp_f32_e32 v184, v156
	v_mul_f32_e32 v156, 0xbfb8aa3b, v185
	v_exp_f32_e32 v156, v156
	v_rcp_f32_e32 v151, v151
	v_rcp_f32_e32 v155, v155
	v_rcp_f32_e32 v182, v182
	v_add_f32_e32 v156, 1.0, v156
	v_rcp_f32_e32 v185, v156
	v_add_u32_e32 v156, 16, v154
	v_ashrrev_i32_e32 v157, 31, v156
	v_lshlrev_b64 v[156:157], 12, v[156:157]
	v_lshl_add_u64 v[156:157], s[72:73], 0, v[156:157]
	v_lshl_add_u64 v[156:157], v[156:157], 0, v[152:153]
	v_cvt_pk_bf16_f32 v182, v151, v182
	v_cvt_pk_bf16_f32 v183, v183, v184
	v_cvt_pk_bf16_f32 v184, v155, v186
	v_cvt_pk_bf16_f32 v185, v187, v185
	global_store_dwordx4 v[156:157], v[182:185], off
	v_pk_add_f32 v[156:157], v[78:79], v[134:135]
	v_pk_add_f32 v[186:187], v[72:73], v[128:129]
	v_pk_add_f32 v[182:183], v[76:77], v[132:133]
	v_mul_f32_e32 v156, 0xbfb8aa3b, v156
	v_mul_f32_e32 v151, 0xbfb8aa3b, v182
	v_mul_f32_e32 v182, 0xbfb8aa3b, v183
	v_mul_f32_e32 v183, 0xbfb8aa3b, v187
	v_exp_f32_e32 v183, v183
	v_exp_f32_e32 v156, v156
	v_pk_add_f32 v[184:185], v[74:75], v[130:131]
	v_mul_f32_e32 v155, 0xbfb8aa3b, v186
	v_add_f32_e32 v183, 1.0, v183
	v_add_f32_e32 v156, 1.0, v156
	v_rcp_f32_e32 v186, v183
	v_rcp_f32_e32 v183, v156
	v_mul_f32_e32 v156, 0xbfb8aa3b, v184
	v_exp_f32_e32 v156, v156
	v_exp_f32_e32 v151, v151
	v_exp_f32_e32 v155, v155
	v_exp_f32_e32 v182, v182
	v_add_f32_e32 v156, 1.0, v156
	v_rcp_f32_e32 v187, v156
	v_mul_f32_e32 v156, 0xbfb8aa3b, v157
	v_exp_f32_e32 v156, v156
	v_add_f32_e32 v151, 1.0, v151
	v_add_f32_e32 v155, 1.0, v155
	v_add_f32_e32 v182, 1.0, v182
	v_add_f32_e32 v156, 1.0, v156
	v_rcp_f32_e32 v184, v156
	v_mul_f32_e32 v156, 0xbfb8aa3b, v185
	v_exp_f32_e32 v156, v156
	v_rcp_f32_e32 v151, v151
	v_rcp_f32_e32 v155, v155
	v_rcp_f32_e32 v182, v182
	v_add_f32_e32 v156, 1.0, v156
	v_rcp_f32_e32 v185, v156
	v_add_u32_e32 v156, 32, v154
	v_ashrrev_i32_e32 v157, 31, v156
	v_lshlrev_b64 v[156:157], 12, v[156:157]
	v_lshl_add_u64 v[156:157], s[72:73], 0, v[156:157]
	v_lshl_add_u64 v[156:157], v[156:157], 0, v[152:153]
	v_cvt_pk_bf16_f32 v182, v151, v182
	v_cvt_pk_bf16_f32 v183, v183, v184
	v_cvt_pk_bf16_f32 v184, v155, v186
	v_cvt_pk_bf16_f32 v185, v187, v185
	global_store_dwordx4 v[156:157], v[182:185], off
	v_pk_add_f32 v[156:157], v[62:63], v[134:135]
	v_pk_add_f32 v[186:187], v[56:57], v[128:129]
	v_pk_add_f32 v[182:183], v[60:61], v[132:133]
	v_mul_f32_e32 v156, 0xbfb8aa3b, v156
	v_mul_f32_e32 v151, 0xbfb8aa3b, v182
	v_mul_f32_e32 v182, 0xbfb8aa3b, v183
	v_mul_f32_e32 v183, 0xbfb8aa3b, v187
	v_exp_f32_e32 v183, v183
	v_exp_f32_e32 v156, v156
	v_pk_add_f32 v[184:185], v[58:59], v[130:131]
	v_mul_f32_e32 v155, 0xbfb8aa3b, v186
	v_add_f32_e32 v183, 1.0, v183
	v_add_f32_e32 v156, 1.0, v156
	v_rcp_f32_e32 v186, v183
	v_rcp_f32_e32 v183, v156
	v_mul_f32_e32 v156, 0xbfb8aa3b, v184
	v_exp_f32_e32 v156, v156
	v_exp_f32_e32 v151, v151
	v_exp_f32_e32 v155, v155
	v_exp_f32_e32 v182, v182
	v_add_f32_e32 v156, 1.0, v156
	v_rcp_f32_e32 v187, v156
	v_mul_f32_e32 v156, 0xbfb8aa3b, v157
	v_exp_f32_e32 v156, v156
	v_add_f32_e32 v151, 1.0, v151
	v_add_f32_e32 v155, 1.0, v155
	v_add_f32_e32 v182, 1.0, v182
	v_add_f32_e32 v156, 1.0, v156
	v_rcp_f32_e32 v184, v156
	v_mul_f32_e32 v156, 0xbfb8aa3b, v185
	v_exp_f32_e32 v156, v156
	v_rcp_f32_e32 v151, v151
	v_rcp_f32_e32 v155, v155
	v_rcp_f32_e32 v182, v182
	v_add_f32_e32 v156, 1.0, v156
	v_rcp_f32_e32 v185, v156
	v_add_u32_e32 v156, 48, v154
	v_ashrrev_i32_e32 v157, 31, v156
	v_lshlrev_b64 v[156:157], 12, v[156:157]
	v_lshl_add_u64 v[156:157], s[72:73], 0, v[156:157]
	v_lshl_add_u64 v[156:157], v[156:157], 0, v[152:153]
	v_cvt_pk_bf16_f32 v182, v151, v182
	v_cvt_pk_bf16_f32 v183, v183, v184
	v_cvt_pk_bf16_f32 v184, v155, v186
	v_cvt_pk_bf16_f32 v185, v187, v185
	global_store_dwordx4 v[156:157], v[182:185], off
	v_pk_add_f32 v[156:157], v[42:43], v[134:135]
	v_pk_add_f32 v[186:187], v[36:37], v[128:129]
	v_pk_add_f32 v[182:183], v[40:41], v[132:133]
	v_mul_f32_e32 v156, 0xbfb8aa3b, v156
	v_mul_f32_e32 v151, 0xbfb8aa3b, v182
	v_mul_f32_e32 v182, 0xbfb8aa3b, v183
	v_mul_f32_e32 v183, 0xbfb8aa3b, v187
	v_exp_f32_e32 v183, v183
	v_exp_f32_e32 v156, v156
	v_pk_add_f32 v[184:185], v[38:39], v[130:131]
	v_mul_f32_e32 v155, 0xbfb8aa3b, v186
	v_add_f32_e32 v183, 1.0, v183
	v_add_f32_e32 v156, 1.0, v156
	v_rcp_f32_e32 v186, v183
	v_rcp_f32_e32 v183, v156
	v_mul_f32_e32 v156, 0xbfb8aa3b, v184
	v_exp_f32_e32 v156, v156
	v_exp_f32_e32 v151, v151
	v_exp_f32_e32 v155, v155
	v_exp_f32_e32 v182, v182
	v_add_f32_e32 v156, 1.0, v156
	v_rcp_f32_e32 v187, v156
	v_mul_f32_e32 v156, 0xbfb8aa3b, v157
	v_exp_f32_e32 v156, v156
	v_add_f32_e32 v151, 1.0, v151
	v_add_f32_e32 v155, 1.0, v155
	v_add_f32_e32 v182, 1.0, v182
	v_add_f32_e32 v156, 1.0, v156
	v_rcp_f32_e32 v184, v156
	v_mul_f32_e32 v156, 0xbfb8aa3b, v185
	v_exp_f32_e32 v156, v156
	v_rcp_f32_e32 v151, v151
	v_rcp_f32_e32 v155, v155
	v_rcp_f32_e32 v182, v182
	v_add_f32_e32 v156, 1.0, v156
	v_rcp_f32_e32 v185, v156
	v_add_u32_e32 v156, 0x80, v154
	v_ashrrev_i32_e32 v157, 31, v156
	v_lshlrev_b64 v[156:157], 12, v[156:157]
	v_lshl_add_u64 v[156:157], s[72:73], 0, v[156:157]
	v_lshl_add_u64 v[156:157], v[156:157], 0, v[152:153]
	v_cvt_pk_bf16_f32 v182, v151, v182
	v_cvt_pk_bf16_f32 v183, v183, v184
	v_cvt_pk_bf16_f32 v184, v155, v186
	v_cvt_pk_bf16_f32 v185, v187, v185
	global_store_dwordx4 v[156:157], v[182:185], off
	v_pk_add_f32 v[156:157], v[30:31], v[134:135]
	v_pk_add_f32 v[186:187], v[20:21], v[128:129]
	v_pk_add_f32 v[182:183], v[28:29], v[132:133]
	v_mul_f32_e32 v156, 0xbfb8aa3b, v156
	v_mul_f32_e32 v151, 0xbfb8aa3b, v182
	v_mul_f32_e32 v182, 0xbfb8aa3b, v183
	v_mul_f32_e32 v183, 0xbfb8aa3b, v187
	v_exp_f32_e32 v183, v183
	v_exp_f32_e32 v156, v156
	v_pk_add_f32 v[184:185], v[22:23], v[130:131]
	v_mul_f32_e32 v155, 0xbfb8aa3b, v186
	v_add_f32_e32 v183, 1.0, v183
	v_add_f32_e32 v156, 1.0, v156
	v_rcp_f32_e32 v186, v183
	v_rcp_f32_e32 v183, v156
	v_mul_f32_e32 v156, 0xbfb8aa3b, v184
	v_exp_f32_e32 v156, v156
	v_exp_f32_e32 v151, v151
	v_exp_f32_e32 v155, v155
	v_exp_f32_e32 v182, v182
	v_add_f32_e32 v156, 1.0, v156
	v_rcp_f32_e32 v187, v156
	v_mul_f32_e32 v156, 0xbfb8aa3b, v157
	v_exp_f32_e32 v156, v156
	v_add_f32_e32 v151, 1.0, v151
	v_add_f32_e32 v155, 1.0, v155
	v_add_f32_e32 v182, 1.0, v182
	v_add_f32_e32 v156, 1.0, v156
	v_rcp_f32_e32 v184, v156
	v_mul_f32_e32 v156, 0xbfb8aa3b, v185
	v_exp_f32_e32 v156, v156
	v_rcp_f32_e32 v151, v151
	v_rcp_f32_e32 v155, v155
	v_rcp_f32_e32 v182, v182
	v_add_f32_e32 v156, 1.0, v156
	v_rcp_f32_e32 v185, v156
	v_add_u32_e32 v156, 0x90, v154
	v_ashrrev_i32_e32 v157, 31, v156
	v_lshlrev_b64 v[156:157], 12, v[156:157]
	v_lshl_add_u64 v[156:157], s[72:73], 0, v[156:157]
	v_lshl_add_u64 v[156:157], v[156:157], 0, v[152:153]
	v_cvt_pk_bf16_f32 v182, v151, v182
	v_cvt_pk_bf16_f32 v183, v183, v184
	v_cvt_pk_bf16_f32 v184, v155, v186
	v_cvt_pk_bf16_f32 v185, v187, v185
	global_store_dwordx4 v[156:157], v[182:185], off
	v_pk_add_f32 v[156:157], v[14:15], v[134:135]
	v_pk_add_f32 v[186:187], v[8:9], v[128:129]
	v_pk_add_f32 v[182:183], v[12:13], v[132:133]
	v_mul_f32_e32 v156, 0xbfb8aa3b, v156
	v_mul_f32_e32 v151, 0xbfb8aa3b, v182
	v_mul_f32_e32 v182, 0xbfb8aa3b, v183
	v_mul_f32_e32 v183, 0xbfb8aa3b, v187
	v_exp_f32_e32 v183, v183
	v_exp_f32_e32 v156, v156
	v_pk_add_f32 v[184:185], v[10:11], v[130:131]
	v_mul_f32_e32 v155, 0xbfb8aa3b, v186
	v_add_f32_e32 v183, 1.0, v183
	v_add_f32_e32 v156, 1.0, v156
	v_rcp_f32_e32 v186, v183
	v_rcp_f32_e32 v183, v156
	v_mul_f32_e32 v156, 0xbfb8aa3b, v184
	v_exp_f32_e32 v156, v156
	v_exp_f32_e32 v155, v155
	v_pk_add_f32 v[128:129], v[0:1], v[128:129]
	v_exp_f32_e32 v151, v151
	v_add_f32_e32 v156, 1.0, v156
	v_rcp_f32_e32 v187, v156
	v_mul_f32_e32 v156, 0xbfb8aa3b, v157
	v_exp_f32_e32 v156, v156
	v_mul_f32_e32 v128, 0xbfb8aa3b, v128
	v_add_f32_e32 v155, 1.0, v155
	v_exp_f32_e32 v128, v128
	v_add_f32_e32 v156, 1.0, v156
	v_rcp_f32_e32 v184, v156
	v_mul_f32_e32 v156, 0xbfb8aa3b, v185
	v_rcp_f32_e32 v155, v155
	v_exp_f32_e32 v182, v182
	v_exp_f32_e32 v156, v156
	v_pk_add_f32 v[132:133], v[4:5], v[132:133]
	v_add_f32_e32 v128, 1.0, v128
	v_add_f32_e32 v151, 1.0, v151
	v_add_f32_e32 v182, 1.0, v182
	v_add_f32_e32 v156, 1.0, v156
	v_cvt_pk_bf16_f32 v183, v183, v184
	v_cvt_pk_bf16_f32 v184, v155, v186
	v_rcp_f32_e32 v155, v128
	v_mul_f32_e32 v128, 0xbfb8aa3b, v133
	v_rcp_f32_e32 v151, v151
	v_rcp_f32_e32 v182, v182
	v_rcp_f32_e32 v185, v156
	v_add_u32_e32 v156, 0xa0, v154
	v_exp_f32_e32 v128, v128
	v_ashrrev_i32_e32 v157, 31, v156
	v_lshlrev_b64 v[156:157], 12, v[156:157]
	v_lshl_add_u64 v[156:157], s[72:73], 0, v[156:157]
	v_lshl_add_u64 v[156:157], v[156:157], 0, v[152:153]
	v_cvt_pk_bf16_f32 v182, v151, v182
	v_cvt_pk_bf16_f32 v185, v187, v185
	v_add_f32_e32 v128, 1.0, v128
	global_store_dwordx4 v[156:157], v[182:185], off
	v_rcp_f32_e32 v156, v128
	v_mul_f32_e32 v128, 0xbfb8aa3b, v129
	v_exp_f32_e32 v128, v128
	v_pk_add_f32 v[134:135], v[6:7], v[134:135]
	v_pk_add_f32 v[130:131], v[2:3], v[130:131]
	v_mul_f32_e32 v132, 0xbfb8aa3b, v132
	v_add_f32_e32 v128, 1.0, v128
	v_rcp_f32_e32 v157, v128
	v_mul_f32_e32 v128, 0xbfb8aa3b, v134
	v_exp_f32_e32 v128, v128
	v_exp_f32_e32 v132, v132
	v_add_f32_e32 v128, 1.0, v128
	v_rcp_f32_e32 v134, v128
	v_mul_f32_e32 v128, 0xbfb8aa3b, v130
	v_exp_f32_e32 v128, v128
	v_add_f32_e32 v132, 1.0, v132
	v_rcp_f32_e32 v151, v132
	v_add_f32_e32 v128, 1.0, v128
	v_rcp_f32_e32 v182, v128
	v_mul_f32_e32 v128, 0xbfb8aa3b, v135
	v_exp_f32_e32 v128, v128
	s_nop 0
	v_add_f32_e32 v128, 1.0, v128
	v_rcp_f32_e32 v130, v128
	v_mul_f32_e32 v128, 0xbfb8aa3b, v131
	v_exp_f32_e32 v128, v128
	s_nop 0
	v_add_f32_e32 v128, 1.0, v128
	v_rcp_f32_e32 v131, v128
	v_add_u32_e32 v128, 0xb0, v154
	v_ashrrev_i32_e32 v129, 31, v128
	v_lshlrev_b64 v[128:129], 12, v[128:129]
	v_lshl_add_u64 v[128:129], s[72:73], 0, v[128:129]
	v_lshl_add_u64 v[132:133], v[128:129], 0, v[152:153]
	v_cvt_pk_bf16_f32 v128, v151, v156
	v_cvt_pk_bf16_f32 v129, v134, v130
	v_cvt_pk_bf16_f32 v130, v155, v157
	v_cvt_pk_bf16_f32 v131, v182, v131
	global_store_dwordx4 v[132:133], v[128:131], off
	s_add_i32 s99, s99, 1

.LBB0_1147:
	s_or_b64 exec, exec, s[6:7]
	s_mov_b32 s99, 3

.LBB0_1149:
	s_cmp_lt_i32 s80, 4
	s_mov_b32 s6, 0x1000000
	s_cselect_b32 s8, s6, 0x2200000
	s_cmp_lt_i32 s80, 2
	s_cselect_b64 vcc, -1, 0
	s_and_b64 s[6:7], vcc, exec
	s_cselect_b32 s6, 0, s8
	s_lshl_b32 s6, s6, 1
	s_add_u32 s6, s64, s6
	s_addc_u32 s7, s65, 0
	s_lshl_b32 s8, s80, 9
	s_and_b32 s8, s8, 0x200
	s_add_u32 s6, s6, s8
	s_addc_u32 s7, s7, 0
	s_lshl_b32 s8, s34, 1
	s_add_u32 s6, s6, s8
	v_lshlrev_b32_e32 v132, 3, v181
	v_ashrrev_i32_e32 v151, 31, v150
	s_addc_u32 s7, s7, 0
	v_ashrrev_i32_e32 v133, 31, v132
	s_ashr_i32 s77, s76, 31
	v_cndmask_b32_e32 v128, 1.0, v180, vcc
	v_lshl_add_u64 v[130:131], v[150:151], 0, s[48:49]
	v_lshl_add_u64 v[132:133], v[132:133], 1, s[6:7]
	s_lshl_b64 s[6:7], s[76:77], 18
	v_lshlrev_b64 v[130:131], 10, v[130:131]
	v_lshl_add_u64 v[132:133], v[132:133], 0, s[6:7]
	s_waitcnt lgkmcnt(0)
	v_pk_mul_f32 v[114:115], v[128:129], v[114:115] op_sel_hi:[0,1]
	v_pk_mul_f32 v[112:113], v[128:129], v[112:113] op_sel_hi:[0,1]
	v_pk_mul_f32 v[126:127], v[128:129], v[126:127] op_sel_hi:[0,1]
	v_pk_mul_f32 v[124:125], v[128:129], v[124:125] op_sel_hi:[0,1]
	v_lshl_add_u64 v[130:131], v[132:133], 0, v[130:131]
	v_cvt_pk_bf16_f32 v112, v112, v113
	v_cvt_pk_bf16_f32 v113, v114, v115
	v_cvt_pk_bf16_f32 v114, v124, v125
	v_cvt_pk_bf16_f32 v115, v126, v127
	global_store_dwordx4 v[130:131], v[112:115], off
	v_pk_mul_f32 v[102:103], v[128:129], v[102:103] op_sel_hi:[0,1]
	v_pk_mul_f32 v[100:101], v[128:129], v[100:101] op_sel_hi:[0,1]
	v_pk_mul_f32 v[112:113], v[128:129], v[98:99] op_sel_hi:[0,1]
	v_pk_mul_f32 v[98:99], v[128:129], v[96:97] op_sel_hi:[0,1]
	v_cvt_pk_bf16_f32 v96, v100, v101
	v_cvt_pk_bf16_f32 v97, v102, v103
	v_cvt_pk_bf16_f32 v98, v98, v99
	v_cvt_pk_bf16_f32 v99, v112, v113
	global_store_dwordx4 v[130:131], v[96:99], off offset:256
	v_pk_mul_f32 v[100:101], v[128:129], v[118:119] op_sel_hi:[0,1]
	s_movk_i32 s6, 0x4000
	v_pk_mul_f32 v[98:99], v[128:129], v[122:123] op_sel_hi:[0,1]
	v_pk_mul_f32 v[96:97], v[128:129], v[120:121] op_sel_hi:[0,1]
	v_pk_mul_f32 v[102:103], v[128:129], v[116:117] op_sel_hi:[0,1]
	v_cvt_pk_bf16_f32 v96, v96, v97
	v_cvt_pk_bf16_f32 v97, v98, v99
	v_cvt_pk_bf16_f32 v99, v100, v101
	v_add_co_u32_e32 v100, vcc, s6, v130
	v_cvt_pk_bf16_f32 v98, v102, v103
	s_nop 0
	v_addc_co_u32_e32 v101, vcc, 0, v131, vcc
	global_store_dwordx4 v[100:101], v[96:99], off
	v_pk_mul_f32 v[86:87], v[128:129], v[86:87] op_sel_hi:[0,1]
	v_pk_mul_f32 v[84:85], v[128:129], v[84:85] op_sel_hi:[0,1]
	v_pk_mul_f32 v[96:97], v[128:129], v[82:83] op_sel_hi:[0,1]
	v_pk_mul_f32 v[82:83], v[128:129], v[80:81] op_sel_hi:[0,1]
	v_cvt_pk_bf16_f32 v80, v84, v85
	v_cvt_pk_bf16_f32 v81, v86, v87
	v_cvt_pk_bf16_f32 v82, v82, v83
	v_cvt_pk_bf16_f32 v83, v96, v97
	global_store_dwordx4 v[100:101], v[80:83], off offset:256
	v_pk_mul_f32 v[84:85], v[128:129], v[106:107] op_sel_hi:[0,1]
	s_mov_b32 s6, 0x8000
	v_pk_mul_f32 v[82:83], v[128:129], v[110:111] op_sel_hi:[0,1]
	v_pk_mul_f32 v[80:81], v[128:129], v[108:109] op_sel_hi:[0,1]
	v_pk_mul_f32 v[86:87], v[128:129], v[104:105] op_sel_hi:[0,1]
	v_cvt_pk_bf16_f32 v80, v80, v81
	v_cvt_pk_bf16_f32 v81, v82, v83
	v_cvt_pk_bf16_f32 v83, v84, v85
	v_add_co_u32_e32 v84, vcc, s6, v130
	v_cvt_pk_bf16_f32 v82, v86, v87
	s_nop 0
	v_addc_co_u32_e32 v85, vcc, 0, v131, vcc
	global_store_dwordx4 v[84:85], v[80:83], off
	v_pk_mul_f32 v[78:79], v[128:129], v[78:79] op_sel_hi:[0,1]
	v_pk_mul_f32 v[76:77], v[128:129], v[76:77] op_sel_hi:[0,1]
	v_pk_mul_f32 v[80:81], v[128:129], v[74:75] op_sel_hi:[0,1]
	v_pk_mul_f32 v[74:75], v[128:129], v[72:73] op_sel_hi:[0,1]
	v_cvt_pk_bf16_f32 v72, v76, v77
	v_cvt_pk_bf16_f32 v73, v78, v79
	v_cvt_pk_bf16_f32 v74, v74, v75
	v_cvt_pk_bf16_f32 v75, v80, v81
	global_store_dwordx4 v[84:85], v[72:75], off offset:256
	v_pk_mul_f32 v[76:77], v[128:129], v[90:91] op_sel_hi:[0,1]
	s_mov_b32 s6, 0xc000
	v_pk_mul_f32 v[74:75], v[128:129], v[94:95] op_sel_hi:[0,1]
	v_pk_mul_f32 v[72:73], v[128:129], v[92:93] op_sel_hi:[0,1]
	v_pk_mul_f32 v[78:79], v[128:129], v[88:89] op_sel_hi:[0,1]
	v_cvt_pk_bf16_f32 v72, v72, v73
	v_cvt_pk_bf16_f32 v73, v74, v75
	v_cvt_pk_bf16_f32 v75, v76, v77
	v_add_co_u32_e32 v76, vcc, s6, v130
	v_cvt_pk_bf16_f32 v74, v78, v79
	s_nop 0
	v_addc_co_u32_e32 v77, vcc, 0, v131, vcc
	global_store_dwordx4 v[76:77], v[72:75], off
	v_pk_mul_f32 v[62:63], v[128:129], v[62:63] op_sel_hi:[0,1]
	v_pk_mul_f32 v[60:61], v[128:129], v[60:61] op_sel_hi:[0,1]
	v_pk_mul_f32 v[72:73], v[128:129], v[58:59] op_sel_hi:[0,1]
	v_pk_mul_f32 v[58:59], v[128:129], v[56:57] op_sel_hi:[0,1]
	v_cvt_pk_bf16_f32 v56, v60, v61
	v_cvt_pk_bf16_f32 v57, v62, v63
	v_cvt_pk_bf16_f32 v58, v58, v59
	v_cvt_pk_bf16_f32 v59, v72, v73
	global_store_dwordx4 v[76:77], v[56:59], off offset:256
	v_pk_mul_f32 v[60:61], v[128:129], v[66:67] op_sel_hi:[0,1]
	s_mov_b32 s6, 0x20000
	v_pk_mul_f32 v[58:59], v[128:129], v[70:71] op_sel_hi:[0,1]
	v_pk_mul_f32 v[56:57], v[128:129], v[68:69] op_sel_hi:[0,1]
	v_pk_mul_f32 v[62:63], v[128:129], v[64:65] op_sel_hi:[0,1]
	v_cvt_pk_bf16_f32 v56, v56, v57
	v_cvt_pk_bf16_f32 v57, v58, v59
	v_cvt_pk_bf16_f32 v59, v60, v61
	v_add_co_u32_e32 v60, vcc, s6, v130
	v_cvt_pk_bf16_f32 v58, v62, v63
	s_nop 0
	v_addc_co_u32_e32 v61, vcc, 0, v131, vcc
	global_store_dwordx4 v[60:61], v[56:59], off
	v_pk_mul_f32 v[42:43], v[128:129], v[42:43] op_sel_hi:[0,1]
	v_pk_mul_f32 v[40:41], v[128:129], v[40:41] op_sel_hi:[0,1]
	v_pk_mul_f32 v[56:57], v[128:129], v[38:39] op_sel_hi:[0,1]
	v_pk_mul_f32 v[38:39], v[128:129], v[36:37] op_sel_hi:[0,1]
	v_cvt_pk_bf16_f32 v36, v40, v41
	v_cvt_pk_bf16_f32 v37, v42, v43
	v_cvt_pk_bf16_f32 v38, v38, v39
	v_cvt_pk_bf16_f32 v39, v56, v57
	global_store_dwordx4 v[60:61], v[36:39], off offset:256
	v_pk_mul_f32 v[40:41], v[128:129], v[50:51] op_sel_hi:[0,1]
	s_mov_b32 s6, 0x24000
	v_pk_mul_f32 v[38:39], v[128:129], v[54:55] op_sel_hi:[0,1]
	v_pk_mul_f32 v[36:37], v[128:129], v[52:53] op_sel_hi:[0,1]
	v_pk_mul_f32 v[42:43], v[128:129], v[48:49] op_sel_hi:[0,1]
	v_cvt_pk_bf16_f32 v36, v36, v37
	v_cvt_pk_bf16_f32 v37, v38, v39
	v_cvt_pk_bf16_f32 v39, v40, v41
	v_add_co_u32_e32 v40, vcc, s6, v130
	v_cvt_pk_bf16_f32 v38, v42, v43
	s_nop 0
	v_addc_co_u32_e32 v41, vcc, 0, v131, vcc
	global_store_dwordx4 v[40:41], v[36:39], off
	v_pk_mul_f32 v[30:31], v[128:129], v[30:31] op_sel_hi:[0,1]
	v_pk_mul_f32 v[28:29], v[128:129], v[28:29] op_sel_hi:[0,1]
	v_pk_mul_f32 v[36:37], v[128:129], v[22:23] op_sel_hi:[0,1]
	v_pk_mul_f32 v[22:23], v[128:129], v[20:21] op_sel_hi:[0,1]
	v_cvt_pk_bf16_f32 v20, v28, v29
	v_cvt_pk_bf16_f32 v21, v30, v31
	v_cvt_pk_bf16_f32 v22, v22, v23
	v_cvt_pk_bf16_f32 v23, v36, v37
	global_store_dwordx4 v[40:41], v[20:23], off offset:256
	v_pk_mul_f32 v[28:29], v[128:129], v[34:35] op_sel_hi:[0,1]
	s_mov_b32 s6, 0x28000
	v_pk_mul_f32 v[22:23], v[128:129], v[46:47] op_sel_hi:[0,1]
	v_pk_mul_f32 v[20:21], v[128:129], v[44:45] op_sel_hi:[0,1]
	v_pk_mul_f32 v[30:31], v[128:129], v[32:33] op_sel_hi:[0,1]
	v_cvt_pk_bf16_f32 v20, v20, v21
	v_cvt_pk_bf16_f32 v21, v22, v23
	v_cvt_pk_bf16_f32 v23, v28, v29
	v_add_co_u32_e32 v28, vcc, s6, v130
	v_cvt_pk_bf16_f32 v22, v30, v31
	s_nop 0
	v_addc_co_u32_e32 v29, vcc, 0, v131, vcc
	global_store_dwordx4 v[28:29], v[20:23], off
	v_pk_mul_f32 v[14:15], v[128:129], v[14:15] op_sel_hi:[0,1]
	v_pk_mul_f32 v[12:13], v[128:129], v[12:13] op_sel_hi:[0,1]
	v_pk_mul_f32 v[20:21], v[128:129], v[10:11] op_sel_hi:[0,1]
	v_pk_mul_f32 v[10:11], v[128:129], v[8:9] op_sel_hi:[0,1]
	v_cvt_pk_bf16_f32 v8, v12, v13
	v_cvt_pk_bf16_f32 v9, v14, v15
	v_cvt_pk_bf16_f32 v10, v10, v11
	v_cvt_pk_bf16_f32 v11, v20, v21
	global_store_dwordx4 v[28:29], v[8:11], off offset:256
	v_pk_mul_f32 v[12:13], v[128:129], v[18:19] op_sel_hi:[0,1]
	s_mov_b32 s6, 0x2c000
	v_pk_mul_f32 v[10:11], v[128:129], v[26:27] op_sel_hi:[0,1]
	v_pk_mul_f32 v[8:9], v[128:129], v[24:25] op_sel_hi:[0,1]
	v_pk_mul_f32 v[14:15], v[128:129], v[16:17] op_sel_hi:[0,1]
	v_cvt_pk_bf16_f32 v8, v8, v9
	v_cvt_pk_bf16_f32 v9, v10, v11
	v_cvt_pk_bf16_f32 v11, v12, v13
	v_add_co_u32_e32 v12, vcc, s6, v130
	v_cvt_pk_bf16_f32 v10, v14, v15
	s_nop 0
	v_addc_co_u32_e32 v13, vcc, 0, v131, vcc
	global_store_dwordx4 v[12:13], v[8:11], off
	v_pk_mul_f32 v[6:7], v[128:129], v[6:7] op_sel_hi:[0,1]
	v_pk_mul_f32 v[4:5], v[128:129], v[4:5] op_sel_hi:[0,1]
	v_pk_mul_f32 v[8:9], v[128:129], v[2:3] op_sel_hi:[0,1]
	v_pk_mul_f32 v[2:3], v[128:129], v[0:1] op_sel_hi:[0,1]
	v_cvt_pk_bf16_f32 v0, v4, v5
	v_cvt_pk_bf16_f32 v1, v6, v7
	v_cvt_pk_bf16_f32 v2, v2, v3
	v_cvt_pk_bf16_f32 v3, v8, v9
	global_store_dwordx4 v[12:13], v[0:3], off offset:256
	s_mov_b32 s99, 3
	s_and_b64 vcc, exec, s[4:5]
	s_mov_b64 s[4:5], -1
	s_cbranch_vccnz .LBB0_1085
